# half-round-tiles-kept-in-owning-XCD+local-barriers-7-8,15-16
# speedup vs baseline: 1.0649x; 1.0019x over previous
.LBB0_347:
	s_add_i32 s87, s79, 0x18000
	v_lshl_add_u64 v[0:1], v[0:1], 0, s[90:91]
	s_mov_b32 m0, s87
	s_add_i32 s94, s79, 0x1a000
	s_waitcnt vmcnt(2)
	s_barrier
	global_load_lds_dwordx4 v[0:1], off
	v_lshl_add_u64 v[0:1], v[2:3], 0, s[90:91]
	s_mov_b32 m0, s94
	s_add_i32 s95, s79, 0x8000
	global_load_lds_dwordx4 v[0:1], off
	v_lshl_add_u64 v[0:1], v[8:9], 0, s[90:91]
	s_mov_b32 m0, s95
	s_add_i32 s96, s79, 0xa000
	global_load_lds_dwordx4 v[0:1], off
	v_lshl_add_u64 v[0:1], v[10:11], 0, s[90:91]
	s_mov_b32 m0, s96
	s_add_i32 s97, s79, 0x1c000
	global_load_lds_dwordx4 v[0:1], off
	v_lshl_add_u64 v[0:1], v[4:5], 0, s[90:91]
	s_mov_b32 m0, s97
	s_add_i32 s98, s79, 0x1e000
	global_load_lds_dwordx4 v[0:1], off
	v_lshl_add_u64 v[0:1], v[6:7], 0, s[90:91]
	s_mov_b32 m0, s98
	v_and_b32_e32 v2, 15, v245
	global_load_lds_dwordx4 v[0:1], off
	v_bfe_u32 v1, v245, 4, 2
	v_lshlrev_b32_e32 v96, 4, v1
	v_lshl_or_b32 v222, s8, 6, v2
	v_lshlrev_b32_e32 v0, 3, v1
	v_lshl_or_b32 v1, v2, 6, v96
	v_lshlrev_b32_e32 v2, 2, v245
	s_lshl_b32 s8, s8, 13
	v_and_b32_e32 v2, 32, v2
	v_bitop3_b32 v3, v1, s8, v2 bitop3:0xde
	s_lshl_b32 s8, s9, 5
	s_and_b32 s8, s8, 0x60
	s_lshl_b32 s9, s8, 7
	v_bitop3_b32 v1, s9, v1, v2 bitop3:0xf6
	v_cvt_f32_u32_e32 v2, s33
	s_bfe_u32 s10, s2, 0x10003
	s_lshr_b32 s76, s74, 6
	s_cmp_gt_u32 s74, 63
	v_rcp_iflag_f32_e32 v2, v2
	s_cselect_b64 s[36:37], -1, 0
	s_add_i32 s99, s76, -2
	v_writelane_b32 v250, s10, 26
	v_mul_f32_e32 v2, 0x4f7ffffe, v2
	v_cvt_u32_f32_e32 v2, v2
	s_cmpk_lt_u32 s7, 0x100
	v_readlane_b32 s10, v252, 26
	s_cselect_b64 s[66:67], -1, 0
	v_readlane_b32 s11, v252, 27
	s_lshl_b32 s42, s18, 1
	s_sub_i32 s9, 0, s33
	v_lshl_add_u64 v[204:205], s[10:11], 0, v[96:97]
	v_readfirstlane_b32 s10, v2
	v_cvt_f32_u32_e32 v2, s42
	s_mul_i32 s9, s9, s10
	s_mul_hi_u32 s9, s10, s9
	s_add_i32 s10, s10, s9
	v_rcp_iflag_f32_e32 v2, v2
	s_mul_hi_u32 s9, s50, s10
	s_lshr_b32 s7, s2, 4
	s_lshl_b32 s7, s7, 3
	s_and_b32 s101, s2, 7
	s_or_b32 s7, s7, s101
	s_mul_i32 s10, s9, s33
	v_writelane_b32 v250, s7, 35
	s_lshr_b32 s7, s50, 3
	s_sub_i32 s10, s50, s10
	s_ashr_i32 s65, s33, 31
	s_and_b32 s17, s50, 7
	s_mov_b32 s54, s7
	s_add_i32 s7, s7, 1
	s_add_i32 s11, s9, 1
	s_sub_i32 s12, s10, s33
	v_mul_f32_e32 v2, 0x4f7ffffe, v2
	s_cmp_ge_u32 s10, s33
	v_cvt_u32_f32_e32 v2, v2
	s_cselect_b32 s9, s11, s9
	s_cselect_b32 s10, s12, s10
	s_add_i32 s11, s9, 1
	s_cmp_ge_u32 s10, s33
	s_cselect_b32 s55, s11, s9
	s_sub_i32 s9, 0, s42
	v_readfirstlane_b32 s10, v2
	v_add_u32_e32 v2, v14, v12
	s_waitcnt vmcnt(6)
	s_mul_i32 s9, s9, s10
	v_add_lshl_u32 v96, v2, v13, 1
	v_add_u32_e32 v2, v17, v15
	s_mul_hi_u32 s9, s10, s9
	v_lshl_add_u64 v[206:207], s[0:1], 0, v[96:97]
	v_add_lshl_u32 v96, v2, v16, 1
	s_mov_b32 s51, s69
	v_writelane_b32 v250, s7, 22
	s_mov_b32 s7, 0
	s_mov_b64 s[12:13], s[36:37]
	s_add_i32 s9, s10, s9
	v_lshl_add_u64 v[208:209], s[0:1], 0, v[96:97]
	s_lshl_b32 s68, s8, 1
	v_lshlrev_b32_e32 v96, 1, v0
	v_add_u32_e32 v223, 0, v1
	v_add_u32_e32 v246, 0, v3
	s_movk_i32 s16, 0x1600
	s_barrier
	v_writelane_b32 v250, s9, 30
	s_branch .LBB0_350

.LBB0_611:
	s_andn2_saveexec_b64 s[4:5], s[30:31]
	s_cbranch_execz .LBB0_24
	s_mov_b64 s[30:31], exec
	s_cmp_eq_u32 s100, 0
	s_cbranch_scc1 .Lglobal_bar
	s_cmp_eq_u32 s73, 3
	s_cbranch_scc1 .Llocal_bar
	s_cmp_eq_u32 s73, 5
	s_cbranch_scc1 .Llocal_bar
	s_cmp_eq_u32 s73, 7
	s_cbranch_scc1 .Llocal_bar
	s_cmp_eq_u32 s73, 11
	s_cbranch_scc1 .Llocal_bar
	s_cmp_eq_u32 s73, 13
	s_cbranch_scc1 .Llocal_bar
	s_cmp_eq_u32 s73, 15
	s_cbranch_scc1 .Llocal_bar
	s_branch .Lglobal_bar
